# P2 interleave selected by XCD parity (vcu bit 5) instead of workgroup parity
# baseline (speedup 1.0000x reference)
; __global__ void __launch_bounds__(NWAVES * 64, 2) mega_fwd(Args args) {
;     ...
;     if (IN(2)) {
;         const float d1 = wave_sum(lq1[lane] * lk1[lane]), d2 = wave_sum(lq2[lane] * lk2[lane]);
;         const float lam = expf(d1) - expf(d2) + 0.2f;
;         const att::SideJob SJ{w_out, w_up, w_dn, g_mlp, WOUT, WUP, WDN, vcu, 256, (G == 256) ? 36 : 0};
;         for (int u = vcu; u < BATCH * NHEAD * 16; u += G) {
;             const int bh = u >> 4, qb = u & 15;
;             datt::diff_unit2<8>(PROJ, KBI, VBI, out, MIX, subg, lam, bh >> 3, bh & 7, qb, (char*)lds + RING_OFF, SJ, (const unsigned*)(ctl + CW_P1D), (G == 256 && N_LAUNCHES != PER_PHASE) ? 256u : 0u);
;         }
;         for (int u = vcu; u < BATCH * NHEAD * 16; u += G) {
;             const int bh = u >> 4, rg = u & 15;
;             att::na_unit<0>(PROJ, MIX, relb, bh >> 3, bh & 7, rg, (char*)lds + RING_OFF);
;         }
.LBB0_395:
	v_readlane_b32 s4, v242, 6
	v_readlane_b32 s5, v242, 7
	s_cmp_lt_i32 s4, 3
	s_cselect_b64 s[0:1], -1, 0
	s_cmp_gt_i32 s5, 2
	s_cselect_b64 s[2:3], -1, 0
	s_and_b64 s[0:1], s[0:1], s[2:3]
	s_andn2_b64 vcc, exec, s[0:1]
	s_cbranch_vccnz .LBB0_628
	v_writelane_b32 v242, 0, 62
	s_bitcmp1_b32 s76, 5
	s_cbranch_scc1 .Lp2_nafirst
